# slot fusion v4: fp8 table conversion of both layers moved out of prep into phase 6 of pass 0 (CU mates alternate convert/GEMM)
# speedup vs baseline: 1.0139x; 1.0063x over previous
; DEVI char* wsp(const Params& P, size_t off) { asm volatile("" : "+s"(off)); return P.ws + off; }
; DEVI int ltid() { int t = threadIdx.x; asm volatile("" : "+v"(t)); return t; }
; DEVI void convert_chunk_fp8(const float* __restrict__ src, unsigned char* __restrict__ dst, float scale, int tid) {
;   int o = tid * 16;
;   uint4 r;
;   unsigned rr[4];
; #pragma unroll
;   for (int q = 0; q < 4; ++q) {
;     float4 a = *reinterpret_cast<const float4*>(src + o + q * 4);
;     int p = __builtin_amdgcn_cvt_pk_fp8_f32(a.x * scale, a.y * scale, 0, false);
;     p = __builtin_amdgcn_cvt_pk_fp8_f32(a.z * scale, a.w * scale, p, true);
;     rr[q] = (unsigned)p;
;   }
;   r = make_uint4(rr[0], rr[1], rr[2], rr[3]);
;   *reinterpret_cast<uint4*>(dst + o) = r;
; }
; DEVI void phase6(const Params& P, int l, int pass, char* smem) {
;   const int tid = ltid();
;   const int ntok = pass ? 8192 : 8448;
;   const int nM = ntok / 128, nN = 8;
;   const bfu* Z = (const bfu*)wsp(P, O_Z);
;   bfu* M = (bfu*)wsp(P, O_CB);
;   for (int id = blockIdx.x; id < nM * nN; id += gridDim.x) {
;     int pm, pn; tile_rc_m(id, nM, nN, pm, pn);
;     float* macc = (float*)wsp(P, O_AU);
;     p6_branch<2, 1, 1>(P, pm, pn, macc, smem, tid);
.LBB0_728:
	s_or_b64 exec, exec, s[26:27]
	s_barrier
	v_readlane_b32 s60, v252, 36
	s_cmp_lg_u32 s60, 0
	s_cbranch_scc1 .Ltb_skip_a
	v_readlane_b32 s60, v252, 32
	s_cmpk_lt_u32 s60, 0x100
	s_cbranch_scc0 .Ltb_skip_a
	v_readlane_b32 s54, v253, 22
	v_readlane_b32 s55, v253, 23
	v_readlane_b32 s56, v253, 24
	v_readlane_b32 s57, v253, 25
	s_lshl_b32 s61, s0, 26
	s_add_u32 s54, s54, s61
	s_addc_u32 s55, s55, 0
	s_add_u32 s56, s56, s61
	s_addc_u32 s57, s57, 0
	v_lshlrev_b32_e32 v248, 6, v93
	v_lshlrev_b32_e32 v250, 4, v93
	v_mov_b32_e32 v251, 0
	v_lshl_add_u64 v[250:251], v[64:65], 0, v[250:251]

; DEVI char* wsp(const Params& P, size_t off) { asm volatile("" : "+s"(off)); return P.ws + off; }
; DEVI void convert_chunk_fp8(const float* __restrict__ src, unsigned char* __restrict__ dst, float scale, int tid) {
;   int o = tid * 16;
;   uint4 r;
;   unsigned rr[4];
; #pragma unroll
;   for (int q = 0; q < 4; ++q) {
;     float4 a = *reinterpret_cast<const float4*>(src + o + q * 4);
;     int p = __builtin_amdgcn_cvt_pk_fp8_f32(a.x * scale, a.y * scale, 0, false);
;     p = __builtin_amdgcn_cvt_pk_fp8_f32(a.z * scale, a.w * scale, p, true);
;     rr[q] = (unsigned)p;
;   }
;   r = make_uint4(rr[0], rr[1], rr[2], rr[3]);
;   *reinterpret_cast<uint4*>(dst + o) = r;
; }
; DEVI void phase6(const Params& P, int l, int pass, char* smem) {
;     ...
;   for (int id = blockIdx.x; id < nM * nN; id += gridDim.x) {
;     int pm, pn; tile_rc_m(id, nM, nN, pm, pn);
;     float* macc = (float*)wsp(P, O_AU);
;     p6_branch<2, 1, 1>(P, pm, pn, macc, smem, tid);
;     p6_branch<1, 2, 0>(P, pm, pn, macc, smem, tid);
;   }
; }
.LBB0_743:
	v_readlane_b32 s60, v252, 36
	s_cmp_lg_u32 s60, 0
	s_cbranch_scc1 .Ltb_skip_b
	v_readlane_b32 s60, v252, 32
	s_cmpk_lt_u32 s60, 0x100
	s_cbranch_scc1 .Ltb_skip_b
	v_readlane_b32 s54, v253, 22
	v_readlane_b32 s55, v253, 23
	v_readlane_b32 s56, v253, 24
	v_readlane_b32 s57, v253, 25
	s_lshl_b32 s61, s0, 26
	s_add_u32 s54, s54, s61
	s_addc_u32 s55, s55, 0
	s_add_u32 s56, s56, s61
	s_addc_u32 s57, s57, 0
	v_lshlrev_b32_e32 v248, 6, v93
	v_lshlrev_b32_e32 v250, 4, v93
	v_mov_b32_e32 v251, 0
	v_lshl_add_u64 v[250:251], v[64:65], 0, v[250:251]
